# EpiGate setup + conv-weight loads hoisted above the pre-epilogue barrier (leading half hides load latency under the barrier wait); peel + trim15 as before
# baseline (speedup 1.0000x reference)
;     __device__ __forceinline__ void operator()(const f32x4 (&acc)[2][2][4][2], const Unit& u, int wr, int wc, int fr, int fq) const {
;         const int ch0 = u.pn * 128 + wc * 32 + 8 * fq;
;         f32x4 w0[2], w1[2], w2[2];
; #pragma unroll
;         for (int n = 0; n < 2; ++n) { w0[n] = *(const f32x4*)(cw + ch0 + 4 * n); w1[n] = *(const f32x4*)(cw + ldh + ch0 + 4 * n); w2[n] = *(const f32x4*)(cw + 2 * ldh + ch0 + 4 * n); }
;         const bool f1 = fr >= 1, f2 = fr >= 2;
; #pragma unroll
;         for (int ai = 0; ai < 2; ++ai) {
;             const int blk = u.pm * 4 + ai * 2 + wr;
; #pragma unroll
;             for (int m = 0; m < 4; ++m) {
;                 const size_t row = (size_t)(u.pm * BM + ai * HALF + wr * 64 + m * 16 + fr);
;                 float hg[8];
; #pragma unroll
;                 for (int n = 0; n < 2; ++n)
; #pragma unroll
;                     for (int i = 0; i < 4; ++i) {
;                         const float cur = acc[ai][0][m][n][i], prv = (m > 0) ? acc[ai][0][m > 0 ? m - 1 : 0][n][i] : cur;
;                         const float r1c = dpp_ror1(cur), r1p = dpp_ror1(prv), r2c = dpp_ror2(cur), r2p = dpp_ror2(prv);
;                         const float tm1 = f1 ? r1c : r1p, tm2 = f2 ? r2c : r2p;
;                         const float cv = w0[n][i] * tm2 + w1[n][i] * tm1 + w2[n][i] * cur;
;                         hg[4 * n + i] = cv * sigmoidf_(cv) * acc[ai][1][m][n][i];
;                     }
;                 if (m == 0 && fr < 2) {
;                     const f32x4 a0 = acc[ai][0][0][0], a1 = acc[ai][0][0][1], v0 = acc[ai][1][0][0], v1 = acc[ai][1][0][1];
;                     u32x4 wa, wv; wa.x = cvt_pk_bf16(a0[0], a0[1]); wa.y = cvt_pk_bf16(a0[2], a0[3]); wa.z = cvt_pk_bf16(a1[0], a1[1]); wa.w = cvt_pk_bf16(a1[2], a1[3]);
;                     wv.x = cvt_pk_bf16(v0[0], v0[1]); wv.y = cvt_pk_bf16(v0[2], v0[3]); wv.z = cvt_pk_bf16(v1[0], v1[1]); wv.w = cvt_pk_bf16(v1[2], v1[3]);
;                     *(u32x4*)(side + ((size_t)blk * 6 + 2 + fr) * ldh + ch0) = wa; *(u32x4*)(side + ((size_t)blk * 6 + 4 + fr) * ldh + ch0) = wv;
;                 } else {
;                     u32x4 w; w.x = cvt_pk_bf16(hg[0], hg[1]); w.y = cvt_pk_bf16(hg[2], hg[3]); w.z = cvt_pk_bf16(hg[4], hg[5]); w.w = cvt_pk_bf16(hg[6], hg[7]);
;                     *(u32x4*)(HG + row * ldh + ch0) = w;
.Lpeel_exit_3:
	v_lshl_or_b32 v70, s15, 7, v221
	v_lshlrev_b32_e32 v71, 2, v70
	global_load_dwordx4 v[224:227], v71, s[52:53]
	global_load_dwordx4 v[228:231], v71, s[52:53] offset:16
	global_load_dwordx4 v[232:235], v71, s[56:57]
	global_load_dwordx4 v[236:239], v71, s[56:57] offset:16
	global_load_dwordx4 v[192:195], v71, s[58:59]
	global_load_dwordx4 v[196:199], v71, s[58:59] offset:16
	s_mov_b32 s65, 0x100000
	v_and_b32_e32 v72, 15, v161
	v_cmp_eq_u32_e64 s[16:17], 15, v72
	v_lshlrev_b32_e32 v188, 1, v70
	v_mov_b32_e32 v189, 0
	v_lshl_add_u32 v73, s14, 8, v161
	v_mad_u64_u32 v[170:171], vcc, v73, s92, v[188:189]
	s_lshl_b32 s14, s14, 2
	s_add_i32 s14, s14, s8
	s_mul_i32 s14, s14, 6
	v_add_u32_e32 v73, s14, v72
	v_lshl_add_u64 v[170:171], s[50:51], 0, v[170:171]
	v_mad_u64_u32 v[190:191], vcc, v73, s92, v[188:189]
	s_mov_b64 s[22:23], exec
	s_mov_b32 s14, 0xbfb8aa3b
	s_mov_b32 s15, 0xbfb8aa3b
	s_mov_b32 s24, 1.0
	s_mov_b32 s25, 1.0
	v_lshl_add_u64 v[190:191], s[48:49], 0, v[190:191]
	s_and_b64 vcc, exec, s[54:55]
	s_cbranch_vccz .LBB0_713
	s_barrier
.LBB0_713:
	s_waitcnt vmcnt(0)
	v_cvt_pk_bf16_f32 v154, v142, v143
	v_cvt_pk_bf16_f32 v155, v144, v145
	v_cvt_pk_bf16_f32 v156, v130, v131
	v_cvt_pk_bf16_f32 v157, v132, v133
	v_cvt_pk_bf16_f32 v204, v150, v151
	v_cvt_pk_bf16_f32 v205, v152, v153
	v_cvt_pk_bf16_f32 v206, v146, v147
	v_cvt_pk_bf16_f32 v207, v148, v149
	v_add_co_u32_e32 v188, vcc, 0xac00, v190
	v_addc_co_u32_e32 v189, vcc, 0, v191, vcc
	v_add_co_u32_e32 v208, vcc, 0x15800, v190
	v_addc_co_u32_e32 v209, vcc, 0, v191, vcc
	s_andn2_b64 exec, s[22:23], s[40:41]
	global_store_dwordx4 v[188:189], v[154:157], off
	global_store_dwordx4 v[208:209], v[204:207], off
	s_mov_b64 exec, s[22:23]
	s_nop 4
	v_pk_mul_f32 v[70:71], v[192:193], v[142:143]
	v_pk_mul_f32 v[72:73], v[194:195], v[144:145]
	v_fmac_f32_dpp v70, v142, v232 row_ror:1 row_mask:0xf bank_mask:0xf
	v_fmac_f32_dpp v71, v143, v233 row_ror:1 row_mask:0xf bank_mask:0xf
	v_fmac_f32_dpp v72, v144, v234 row_ror:1 row_mask:0xf bank_mask:0xf
	v_fmac_f32_dpp v73, v145, v235 row_ror:1 row_mask:0xf bank_mask:0xf
	v_fmac_f32_dpp v70, v142, v224 row_ror:2 row_mask:0xf bank_mask:0xf
	v_fmac_f32_dpp v71, v143, v225 row_ror:2 row_mask:0xf bank_mask:0xf
	v_fmac_f32_dpp v72, v144, v226 row_ror:2 row_mask:0xf bank_mask:0xf
	v_fmac_f32_dpp v73, v145, v227 row_ror:2 row_mask:0xf bank_mask:0xf
	v_pk_mul_f32 v[200:201], v[70:71], s[14:15]
	v_pk_mul_f32 v[202:203], v[72:73], s[14:15]
	v_exp_f32_e32 v200, v200
	v_exp_f32_e32 v201, v201
	v_exp_f32_e32 v202, v202
	v_exp_f32_e32 v203, v203
	v_pk_add_f32 v[200:201], v[200:201], s[24:25]
	v_pk_add_f32 v[202:203], v[202:203], s[24:25]
	v_rcp_f32_e32 v200, v200
	v_rcp_f32_e32 v201, v201
	v_rcp_f32_e32 v202, v202
	v_rcp_f32_e32 v203, v203
	v_pk_mul_f32 v[70:71], v[70:71], v[200:201]
	v_pk_mul_f32 v[72:73], v[72:73], v[202:203]
	v_pk_mul_f32 v[150:151], v[150:151], v[70:71]
	v_pk_mul_f32 v[152:153], v[152:153], v[72:73]
	v_pk_mul_f32 v[70:71], v[196:197], v[130:131]
	v_pk_mul_f32 v[72:73], v[198:199], v[132:133]
	v_fmac_f32_dpp v70, v130, v236 row_ror:1 row_mask:0xf bank_mask:0xf
	v_fmac_f32_dpp v71, v131, v237 row_ror:1 row_mask:0xf bank_mask:0xf
	v_fmac_f32_dpp v72, v132, v238 row_ror:1 row_mask:0xf bank_mask:0xf
	v_fmac_f32_dpp v73, v133, v239 row_ror:1 row_mask:0xf bank_mask:0xf
	v_fmac_f32_dpp v70, v130, v228 row_ror:2 row_mask:0xf bank_mask:0xf
	v_fmac_f32_dpp v71, v131, v229 row_ror:2 row_mask:0xf bank_mask:0xf
	v_fmac_f32_dpp v72, v132, v230 row_ror:2 row_mask:0xf bank_mask:0xf
	v_fmac_f32_dpp v73, v133, v231 row_ror:2 row_mask:0xf bank_mask:0xf
	v_pk_mul_f32 v[200:201], v[70:71], s[14:15]
	v_pk_mul_f32 v[202:203], v[72:73], s[14:15]
	v_exp_f32_e32 v200, v200
	v_exp_f32_e32 v201, v201
	v_exp_f32_e32 v202, v202
	v_exp_f32_e32 v203, v203
	v_pk_add_f32 v[200:201], v[200:201], s[24:25]
	v_pk_add_f32 v[202:203], v[202:203], s[24:25]
	v_rcp_f32_e32 v200, v200
	v_rcp_f32_e32 v201, v201
	v_rcp_f32_e32 v202, v202
	v_rcp_f32_e32 v203, v203
	v_pk_mul_f32 v[70:71], v[70:71], v[200:201]
	v_pk_mul_f32 v[72:73], v[72:73], v[202:203]
	v_pk_mul_f32 v[146:147], v[146:147], v[70:71]
	v_pk_mul_f32 v[148:149], v[148:149], v[72:73]
	v_cvt_pk_bf16_f32 v150, v150, v151
	v_cvt_pk_bf16_f32 v151, v152, v153
	v_cvt_pk_bf16_f32 v152, v146, v147
	v_cvt_pk_bf16_f32 v153, v148, v149
	s_and_b64 exec, s[22:23], s[40:41]
	global_store_dwordx4 v[170:171], v[150:153], off
	s_mov_b64 exec, s[22:23]
	v_cndmask_b32_e64 v200, v138, v142, s[16:17]
	v_cndmask_b32_e64 v201, v139, v143, s[16:17]
	v_cndmask_b32_e64 v202, v140, v144, s[16:17]
	v_cndmask_b32_e64 v203, v141, v145, s[16:17]
	v_cndmask_b32_e64 v204, v138, v142, s[42:43]
	v_cndmask_b32_e64 v205, v139, v143, s[42:43]
	v_cndmask_b32_e64 v206, v140, v144, s[42:43]
	v_cndmask_b32_e64 v207, v141, v145, s[42:43]
	v_pk_mul_f32 v[70:71], v[192:193], v[138:139]
	v_pk_mul_f32 v[72:73], v[194:195], v[140:141]
	v_fmac_f32_dpp v70, v200, v232 row_ror:1 row_mask:0xf bank_mask:0xf
	v_fmac_f32_dpp v71, v201, v233 row_ror:1 row_mask:0xf bank_mask:0xf
	v_fmac_f32_dpp v72, v202, v234 row_ror:1 row_mask:0xf bank_mask:0xf
	v_fmac_f32_dpp v73, v203, v235 row_ror:1 row_mask:0xf bank_mask:0xf
	v_fmac_f32_dpp v70, v204, v224 row_ror:2 row_mask:0xf bank_mask:0xf
	v_fmac_f32_dpp v71, v205, v225 row_ror:2 row_mask:0xf bank_mask:0xf
	v_fmac_f32_dpp v72, v206, v226 row_ror:2 row_mask:0xf bank_mask:0xf
	v_fmac_f32_dpp v73, v207, v227 row_ror:2 row_mask:0xf bank_mask:0xf
	v_pk_mul_f32 v[200:201], v[70:71], s[14:15]
	v_pk_mul_f32 v[202:203], v[72:73], s[14:15]
	v_exp_f32_e32 v200, v200
	v_exp_f32_e32 v201, v201
	v_exp_f32_e32 v202, v202
	v_exp_f32_e32 v203, v203
; __device__ __forceinline__ unsigned cvt_pk_bf16(float lo, float hi) { unsigned r; asm volatile("v_cvt_pk_bf16_f32 %0, %1, %2" : "=v"(r) : "v"(lo), "v"(hi)); return r; }
; __device__ __forceinline__ float sigmoidf_(float x) { return __builtin_amdgcn_rcpf(1.0f + __expf(-x)); }
; __device__ __forceinline__ float dpp_ror1(float x) { return __int_as_float(__builtin_amdgcn_update_dpp(0, __float_as_int(x), 0x121, 0xF, 0xF, true)); }
; __device__ __forceinline__ float dpp_ror2(float x) { return __int_as_float(__builtin_amdgcn_update_dpp(0, __float_as_int(x), 0x122, 0xF, 0xF, true)); }
;     __device__ __forceinline__ void operator()(const f32x4 (&acc)[2][2][4][2], const Unit& u, int wr, int wc, int fr, int fq) const {
;     ...
;                 for (int n = 0; n < 2; ++n)
; #pragma unroll
;                     for (int i = 0; i < 4; ++i) {
;                         const float cur = acc[ai][0][m][n][i], prv = (m > 0) ? acc[ai][0][m > 0 ? m - 1 : 0][n][i] : cur;
;                         const float r1c = dpp_ror1(cur), r1p = dpp_ror1(prv), r2c = dpp_ror2(cur), r2p = dpp_ror2(prv);
;                         const float tm1 = f1 ? r1c : r1p, tm2 = f2 ? r2c : r2p;
;                         const float cv = w0[n][i] * tm2 + w1[n][i] * tm1 + w2[n][i] * cur;
;                         hg[4 * n + i] = cv * sigmoidf_(cv) * acc[ai][1][m][n][i];
;                     }
;                 if (m == 0 && fr < 2) {
;                     const f32x4 a0 = acc[ai][0][0][0], a1 = acc[ai][0][0][1], v0 = acc[ai][1][0][0], v1 = acc[ai][1][0][1];
;                     u32x4 wa, wv; wa.x = cvt_pk_bf16(a0[0], a0[1]); wa.y = cvt_pk_bf16(a0[2], a0[3]); wa.z = cvt_pk_bf16(a1[0], a1[1]); wa.w = cvt_pk_bf16(a1[2], a1[3]);
;                     wv.x = cvt_pk_bf16(v0[0], v0[1]); wv.y = cvt_pk_bf16(v0[2], v0[3]); wv.z = cvt_pk_bf16(v1[0], v1[1]); wv.w = cvt_pk_bf16(v1[2], v1[3]);
;                     *(u32x4*)(side + ((size_t)blk * 6 + 2 + fr) * ldh + ch0) = wa; *(u32x4*)(side + ((size_t)blk * 6 + 4 + fr) * ldh + ch0) = wv;
;                 } else {
;                     u32x4 w; w.x = cvt_pk_bf16(hg[0], hg[1]); w.y = cvt_pk_bf16(hg[2], hg[3]); w.z = cvt_pk_bf16(hg[4], hg[5]); w.w = cvt_pk_bf16(hg[6], hg[7]);
;                     *(u32x4*)(HG + row * ldh + ch0) = w;
	v_pk_add_f32 v[200:201], v[200:201], s[24:25]
	v_pk_add_f32 v[202:203], v[202:203], s[24:25]
	v_rcp_f32_e32 v200, v200
	v_rcp_f32_e32 v201, v201
	v_rcp_f32_e32 v202, v202
	v_rcp_f32_e32 v203, v203
	v_pk_mul_f32 v[70:71], v[70:71], v[200:201]
	v_pk_mul_f32 v[72:73], v[72:73], v[202:203]
	v_pk_mul_f32 v[134:135], v[134:135], v[70:71]
	v_pk_mul_f32 v[136:137], v[136:137], v[72:73]
	v_cndmask_b32_e64 v200, v126, v130, s[16:17]
	v_cndmask_b32_e64 v201, v127, v131, s[16:17]
	v_cndmask_b32_e64 v202, v128, v132, s[16:17]
	v_cndmask_b32_e64 v203, v129, v133, s[16:17]
	v_cndmask_b32_e64 v204, v126, v130, s[42:43]
	v_cndmask_b32_e64 v205, v127, v131, s[42:43]
	v_cndmask_b32_e64 v206, v128, v132, s[42:43]
	v_cndmask_b32_e64 v207, v129, v133, s[42:43]
	v_pk_mul_f32 v[70:71], v[196:197], v[126:127]
	v_pk_mul_f32 v[72:73], v[198:199], v[128:129]
	v_fmac_f32_dpp v70, v200, v236 row_ror:1 row_mask:0xf bank_mask:0xf
	v_fmac_f32_dpp v71, v201, v237 row_ror:1 row_mask:0xf bank_mask:0xf
	v_fmac_f32_dpp v72, v202, v238 row_ror:1 row_mask:0xf bank_mask:0xf
	v_fmac_f32_dpp v73, v203, v239 row_ror:1 row_mask:0xf bank_mask:0xf
	v_fmac_f32_dpp v70, v204, v228 row_ror:2 row_mask:0xf bank_mask:0xf
	v_fmac_f32_dpp v71, v205, v229 row_ror:2 row_mask:0xf bank_mask:0xf
	v_fmac_f32_dpp v72, v206, v230 row_ror:2 row_mask:0xf bank_mask:0xf
	v_fmac_f32_dpp v73, v207, v231 row_ror:2 row_mask:0xf bank_mask:0xf
	v_pk_mul_f32 v[200:201], v[70:71], s[14:15]
	v_pk_mul_f32 v[202:203], v[72:73], s[14:15]
	v_exp_f32_e32 v200, v200
	v_exp_f32_e32 v201, v201
	v_exp_f32_e32 v202, v202
	v_exp_f32_e32 v203, v203
	v_pk_add_f32 v[200:201], v[200:201], s[24:25]
	v_pk_add_f32 v[202:203], v[202:203], s[24:25]
	v_rcp_f32_e32 v200, v200
	v_rcp_f32_e32 v201, v201
	v_rcp_f32_e32 v202, v202
	v_rcp_f32_e32 v203, v203
	v_pk_mul_f32 v[70:71], v[70:71], v[200:201]
	v_pk_mul_f32 v[72:73], v[72:73], v[202:203]
	v_pk_mul_f32 v[122:123], v[122:123], v[70:71]
	v_pk_mul_f32 v[124:125], v[124:125], v[72:73]
	v_cvt_pk_bf16_f32 v134, v134, v135
	v_cvt_pk_bf16_f32 v135, v136, v137
	v_cvt_pk_bf16_f32 v136, v122, v123
	v_cvt_pk_bf16_f32 v137, v124, v125
	v_add_co_u32_e32 v170, vcc, 0x56000, v170
	v_addc_co_u32_e32 v171, vcc, 0, v171, vcc
	global_store_dwordx4 v[170:171], v[134:137], off
	v_cndmask_b32_e64 v200, v118, v138, s[16:17]
	v_cndmask_b32_e64 v201, v119, v139, s[16:17]
	v_cndmask_b32_e64 v202, v120, v140, s[16:17]
	v_cndmask_b32_e64 v203, v121, v141, s[16:17]
	v_cndmask_b32_e64 v204, v118, v138, s[42:43]
	v_cndmask_b32_e64 v205, v119, v139, s[42:43]
	v_cndmask_b32_e64 v206, v120, v140, s[42:43]
	v_cndmask_b32_e64 v207, v121, v141, s[42:43]
	v_pk_mul_f32 v[70:71], v[192:193], v[118:119]
	v_pk_mul_f32 v[72:73], v[194:195], v[120:121]
	v_fmac_f32_dpp v70, v200, v232 row_ror:1 row_mask:0xf bank_mask:0xf
	v_fmac_f32_dpp v71, v201, v233 row_ror:1 row_mask:0xf bank_mask:0xf
	v_fmac_f32_dpp v72, v202, v234 row_ror:1 row_mask:0xf bank_mask:0xf
	v_fmac_f32_dpp v73, v203, v235 row_ror:1 row_mask:0xf bank_mask:0xf
	v_fmac_f32_dpp v70, v204, v224 row_ror:2 row_mask:0xf bank_mask:0xf
	v_fmac_f32_dpp v71, v205, v225 row_ror:2 row_mask:0xf bank_mask:0xf
	v_fmac_f32_dpp v72, v206, v226 row_ror:2 row_mask:0xf bank_mask:0xf
	v_fmac_f32_dpp v73, v207, v227 row_ror:2 row_mask:0xf bank_mask:0xf
	v_pk_mul_f32 v[200:201], v[70:71], s[14:15]
	v_pk_mul_f32 v[202:203], v[72:73], s[14:15]
	v_exp_f32_e32 v200, v200
	v_exp_f32_e32 v201, v201
	v_exp_f32_e32 v202, v202
	v_exp_f32_e32 v203, v203
	v_pk_add_f32 v[200:201], v[200:201], s[24:25]
	v_pk_add_f32 v[202:203], v[202:203], s[24:25]
	v_rcp_f32_e32 v200, v200
	v_rcp_f32_e32 v201, v201
	v_rcp_f32_e32 v202, v202
	v_rcp_f32_e32 v203, v203
	v_pk_mul_f32 v[70:71], v[70:71], v[200:201]
	v_pk_mul_f32 v[72:73], v[72:73], v[202:203]
	v_pk_mul_f32 v[114:115], v[114:115], v[70:71]
	v_pk_mul_f32 v[116:117], v[116:117], v[72:73]
	v_cndmask_b32_e64 v200, v110, v126, s[16:17]
	v_cndmask_b32_e64 v201, v111, v127, s[16:17]
	v_cndmask_b32_e64 v202, v112, v128, s[16:17]
	v_cndmask_b32_e64 v203, v113, v129, s[16:17]
	v_cndmask_b32_e64 v204, v110, v126, s[42:43]
	v_cndmask_b32_e64 v205, v111, v127, s[42:43]
	v_cndmask_b32_e64 v206, v112, v128, s[42:43]
	v_cndmask_b32_e64 v207, v113, v129, s[42:43]
	v_pk_mul_f32 v[70:71], v[196:197], v[110:111]
	v_pk_mul_f32 v[72:73], v[198:199], v[112:113]
	v_fmac_f32_dpp v70, v200, v236 row_ror:1 row_mask:0xf bank_mask:0xf
	v_fmac_f32_dpp v71, v201, v237 row_ror:1 row_mask:0xf bank_mask:0xf
	v_fmac_f32_dpp v72, v202, v238 row_ror:1 row_mask:0xf bank_mask:0xf
	v_fmac_f32_dpp v73, v203, v239 row_ror:1 row_mask:0xf bank_mask:0xf
	v_fmac_f32_dpp v70, v204, v228 row_ror:2 row_mask:0xf bank_mask:0xf
	v_fmac_f32_dpp v71, v205, v229 row_ror:2 row_mask:0xf bank_mask:0xf
	v_fmac_f32_dpp v72, v206, v230 row_ror:2 row_mask:0xf bank_mask:0xf
	v_fmac_f32_dpp v73, v207, v231 row_ror:2 row_mask:0xf bank_mask:0xf
	v_pk_mul_f32 v[200:201], v[70:71], s[14:15]
	v_pk_mul_f32 v[202:203], v[72:73], s[14:15]
	v_exp_f32_e32 v200, v200
	v_exp_f32_e32 v201, v201
	v_exp_f32_e32 v202, v202
	v_exp_f32_e32 v203, v203
	v_pk_add_f32 v[200:201], v[200:201], s[24:25]
	v_pk_add_f32 v[202:203], v[202:203], s[24:25]
	v_rcp_f32_e32 v200, v200
	v_rcp_f32_e32 v201, v201
	v_rcp_f32_e32 v202, v202
	v_rcp_f32_e32 v203, v203
	v_pk_mul_f32 v[70:71], v[70:71], v[200:201]
	v_pk_mul_f32 v[72:73], v[72:73], v[202:203]
	v_pk_mul_f32 v[106:107], v[106:107], v[70:71]
	v_pk_mul_f32 v[108:109], v[108:109], v[72:73]
	v_cvt_pk_bf16_f32 v114, v114, v115
	v_cvt_pk_bf16_f32 v115, v116, v117
	v_cvt_pk_bf16_f32 v116, v106, v107
	v_cvt_pk_bf16_f32 v117, v108, v109
	v_add_co_u32_e32 v170, vcc, 0x56000, v170
; __device__ __forceinline__ unsigned cvt_pk_bf16(float lo, float hi) { unsigned r; asm volatile("v_cvt_pk_bf16_f32 %0, %1, %2" : "=v"(r) : "v"(lo), "v"(hi)); return r; }
; __device__ __forceinline__ float sigmoidf_(float x) { return __builtin_amdgcn_rcpf(1.0f + __expf(-x)); }
;     __device__ __forceinline__ void operator()(const f32x4 (&acc)[2][2][4][2], const Unit& u, int wr, int wc, int fr, int fq) const {
;     ...
;                 for (int n = 0; n < 2; ++n)
; #pragma unroll
;                     for (int i = 0; i < 4; ++i) {
;                         const float cur = acc[ai][0][m][n][i], prv = (m > 0) ? acc[ai][0][m > 0 ? m - 1 : 0][n][i] : cur;
;                         const float r1c = dpp_ror1(cur), r1p = dpp_ror1(prv), r2c = dpp_ror2(cur), r2p = dpp_ror2(prv);
;                         const float tm1 = f1 ? r1c : r1p, tm2 = f2 ? r2c : r2p;
;                         const float cv = w0[n][i] * tm2 + w1[n][i] * tm1 + w2[n][i] * cur;
;                         hg[4 * n + i] = cv * sigmoidf_(cv) * acc[ai][1][m][n][i];
;                     }
;                 if (m == 0 && fr < 2) {
;                     const f32x4 a0 = acc[ai][0][0][0], a1 = acc[ai][0][0][1], v0 = acc[ai][1][0][0], v1 = acc[ai][1][0][1];
;                     u32x4 wa, wv; wa.x = cvt_pk_bf16(a0[0], a0[1]); wa.y = cvt_pk_bf16(a0[2], a0[3]); wa.z = cvt_pk_bf16(a1[0], a1[1]); wa.w = cvt_pk_bf16(a1[2], a1[3]);
;                     wv.x = cvt_pk_bf16(v0[0], v0[1]); wv.y = cvt_pk_bf16(v0[2], v0[3]); wv.z = cvt_pk_bf16(v1[0], v1[1]); wv.w = cvt_pk_bf16(v1[2], v1[3]);
;                     *(u32x4*)(side + ((size_t)blk * 6 + 2 + fr) * ldh + ch0) = wa; *(u32x4*)(side + ((size_t)blk * 6 + 4 + fr) * ldh + ch0) = wv;
;                 } else {
;                     u32x4 w; w.x = cvt_pk_bf16(hg[0], hg[1]); w.y = cvt_pk_bf16(hg[2], hg[3]); w.z = cvt_pk_bf16(hg[4], hg[5]); w.w = cvt_pk_bf16(hg[6], hg[7]);
;                     *(u32x4*)(HG + row * ldh + ch0) = w;
;                 }
;                 if (m == 3 && fr >= 14) {
;                     const f32x4 a0 = acc[ai][0][3][0], a1 = acc[ai][0][3][1];
;                     u32x4 wa; wa.x = cvt_pk_bf16(a0[0], a0[1]); wa.y = cvt_pk_bf16(a0[2], a0[3]); wa.z = cvt_pk_bf16(a1[0], a1[1]); wa.w = cvt_pk_bf16(a1[2], a1[3]);
;                     *(u32x4*)(side + ((size_t)blk * 6 + (fr - 14)) * ldh + ch0) = wa;
;                 }
	v_addc_co_u32_e32 v171, vcc, 0, v171, vcc
	global_store_dwordx4 v[170:171], v[114:117], off
	v_cndmask_b32_e64 v200, v98, v118, s[16:17]
	v_cndmask_b32_e64 v201, v99, v119, s[16:17]
	v_cndmask_b32_e64 v202, v100, v120, s[16:17]
	v_cndmask_b32_e64 v203, v101, v121, s[16:17]
	v_cndmask_b32_e64 v204, v98, v118, s[42:43]
	v_cndmask_b32_e64 v205, v99, v119, s[42:43]
	v_cndmask_b32_e64 v206, v100, v120, s[42:43]
	v_cndmask_b32_e64 v207, v101, v121, s[42:43]
	v_pk_mul_f32 v[70:71], v[192:193], v[98:99]
	v_pk_mul_f32 v[72:73], v[194:195], v[100:101]
	v_fmac_f32_dpp v70, v200, v232 row_ror:1 row_mask:0xf bank_mask:0xf
	v_fmac_f32_dpp v71, v201, v233 row_ror:1 row_mask:0xf bank_mask:0xf
	v_fmac_f32_dpp v72, v202, v234 row_ror:1 row_mask:0xf bank_mask:0xf
	v_fmac_f32_dpp v73, v203, v235 row_ror:1 row_mask:0xf bank_mask:0xf
	v_fmac_f32_dpp v70, v204, v224 row_ror:2 row_mask:0xf bank_mask:0xf
	v_fmac_f32_dpp v71, v205, v225 row_ror:2 row_mask:0xf bank_mask:0xf
	v_fmac_f32_dpp v72, v206, v226 row_ror:2 row_mask:0xf bank_mask:0xf
	v_fmac_f32_dpp v73, v207, v227 row_ror:2 row_mask:0xf bank_mask:0xf
	v_pk_mul_f32 v[200:201], v[70:71], s[14:15]
	v_pk_mul_f32 v[202:203], v[72:73], s[14:15]
	v_exp_f32_e32 v200, v200
	v_exp_f32_e32 v201, v201
	v_exp_f32_e32 v202, v202
	v_exp_f32_e32 v203, v203
	v_pk_add_f32 v[200:201], v[200:201], s[24:25]
	v_pk_add_f32 v[202:203], v[202:203], s[24:25]
	v_rcp_f32_e32 v200, v200
	v_rcp_f32_e32 v201, v201
	v_rcp_f32_e32 v202, v202
	v_rcp_f32_e32 v203, v203
	v_pk_mul_f32 v[70:71], v[70:71], v[200:201]
	v_pk_mul_f32 v[72:73], v[72:73], v[202:203]
	v_pk_mul_f32 v[102:103], v[102:103], v[70:71]
	v_pk_mul_f32 v[104:105], v[104:105], v[72:73]
	v_cndmask_b32_e64 v200, v94, v110, s[16:17]
	v_cndmask_b32_e64 v201, v95, v111, s[16:17]
	v_cndmask_b32_e64 v202, v96, v112, s[16:17]
	v_cndmask_b32_e64 v203, v97, v113, s[16:17]
	v_cndmask_b32_e64 v204, v94, v110, s[42:43]
	v_cndmask_b32_e64 v205, v95, v111, s[42:43]
	v_cndmask_b32_e64 v206, v96, v112, s[42:43]
	v_cndmask_b32_e64 v207, v97, v113, s[42:43]
	v_pk_mul_f32 v[70:71], v[196:197], v[94:95]
	v_pk_mul_f32 v[72:73], v[198:199], v[96:97]
	v_fmac_f32_dpp v70, v200, v236 row_ror:1 row_mask:0xf bank_mask:0xf
	v_fmac_f32_dpp v71, v201, v237 row_ror:1 row_mask:0xf bank_mask:0xf
	v_fmac_f32_dpp v72, v202, v238 row_ror:1 row_mask:0xf bank_mask:0xf
	v_fmac_f32_dpp v73, v203, v239 row_ror:1 row_mask:0xf bank_mask:0xf
	v_fmac_f32_dpp v70, v204, v228 row_ror:2 row_mask:0xf bank_mask:0xf
	v_fmac_f32_dpp v71, v205, v229 row_ror:2 row_mask:0xf bank_mask:0xf
	v_fmac_f32_dpp v72, v206, v230 row_ror:2 row_mask:0xf bank_mask:0xf
	v_fmac_f32_dpp v73, v207, v231 row_ror:2 row_mask:0xf bank_mask:0xf
	v_pk_mul_f32 v[200:201], v[70:71], s[14:15]
	v_pk_mul_f32 v[202:203], v[72:73], s[14:15]
	v_exp_f32_e32 v200, v200
	v_exp_f32_e32 v201, v201
	v_exp_f32_e32 v202, v202
	v_exp_f32_e32 v203, v203
	v_pk_add_f32 v[200:201], v[200:201], s[24:25]
	v_pk_add_f32 v[202:203], v[202:203], s[24:25]
	v_rcp_f32_e32 v200, v200
	v_rcp_f32_e32 v201, v201
	v_rcp_f32_e32 v202, v202
	v_rcp_f32_e32 v203, v203
	v_pk_mul_f32 v[70:71], v[70:71], v[200:201]
	v_pk_mul_f32 v[72:73], v[72:73], v[202:203]
	v_pk_mul_f32 v[90:91], v[90:91], v[70:71]
	v_pk_mul_f32 v[92:93], v[92:93], v[72:73]
	v_cvt_pk_bf16_f32 v102, v102, v103
	v_cvt_pk_bf16_f32 v103, v104, v105
	v_cvt_pk_bf16_f32 v104, v90, v91
	v_cvt_pk_bf16_f32 v105, v92, v93
	v_add_co_u32_e32 v170, vcc, 0x56000, v170
	v_addc_co_u32_e32 v171, vcc, 0, v171, vcc
	global_store_dwordx4 v[170:171], v[102:105], off
	v_cvt_pk_bf16_f32 v154, v98, v99
	v_cvt_pk_bf16_f32 v155, v100, v101
	v_cvt_pk_bf16_f32 v156, v94, v95
	v_cvt_pk_bf16_f32 v157, v96, v97
	v_add_co_u32_e32 v188, vcc, 0xfffb4c00, v190
	v_addc_co_u32_e32 v189, vcc, -1, v191, vcc
	s_and_b64 exec, s[22:23], s[42:43]
	global_store_dwordx4 v[188:189], v[154:157], off
	s_mov_b64 exec, s[22:23]
	v_cvt_pk_bf16_f32 v154, v62, v63
	v_cvt_pk_bf16_f32 v155, v64, v65
	v_cvt_pk_bf16_f32 v156, v42, v43
	v_cvt_pk_bf16_f32 v157, v44, v45
	v_cvt_pk_bf16_f32 v204, v82, v83
	v_cvt_pk_bf16_f32 v205, v84, v85
	v_cvt_pk_bf16_f32 v206, v78, v79
	v_cvt_pk_bf16_f32 v207, v80, v81
	v_add_co_u32_e32 v188, vcc, 0x4b400, v190
	v_addc_co_u32_e32 v189, vcc, 0, v191, vcc
	v_add_co_u32_e32 v208, vcc, 0x56000, v190
	v_addc_co_u32_e32 v209, vcc, 0, v191, vcc
	s_andn2_b64 exec, s[22:23], s[40:41]
	global_store_dwordx4 v[188:189], v[154:157], off
	global_store_dwordx4 v[208:209], v[204:207], off
	s_mov_b64 exec, s[22:23]
	s_nop 4
	v_pk_mul_f32 v[70:71], v[192:193], v[62:63]
	v_pk_mul_f32 v[72:73], v[194:195], v[64:65]
	v_fmac_f32_dpp v70, v62, v232 row_ror:1 row_mask:0xf bank_mask:0xf
	v_fmac_f32_dpp v71, v63, v233 row_ror:1 row_mask:0xf bank_mask:0xf
	v_fmac_f32_dpp v72, v64, v234 row_ror:1 row_mask:0xf bank_mask:0xf
	v_fmac_f32_dpp v73, v65, v235 row_ror:1 row_mask:0xf bank_mask:0xf
	v_fmac_f32_dpp v70, v62, v224 row_ror:2 row_mask:0xf bank_mask:0xf
	v_fmac_f32_dpp v71, v63, v225 row_ror:2 row_mask:0xf bank_mask:0xf
	v_fmac_f32_dpp v72, v64, v226 row_ror:2 row_mask:0xf bank_mask:0xf
	v_fmac_f32_dpp v73, v65, v227 row_ror:2 row_mask:0xf bank_mask:0xf
	v_pk_mul_f32 v[200:201], v[70:71], s[14:15]
	v_pk_mul_f32 v[202:203], v[72:73], s[14:15]
	v_exp_f32_e32 v200, v200
	v_exp_f32_e32 v201, v201
	v_exp_f32_e32 v202, v202
	v_exp_f32_e32 v203, v203
	v_pk_add_f32 v[200:201], v[200:201], s[24:25]
	v_pk_add_f32 v[202:203], v[202:203], s[24:25]
	v_rcp_f32_e32 v200, v200
	v_rcp_f32_e32 v201, v201
	v_rcp_f32_e32 v202, v202
	v_rcp_f32_e32 v203, v203
	v_pk_mul_f32 v[70:71], v[70:71], v[200:201]
	v_pk_mul_f32 v[72:73], v[72:73], v[202:203]
	v_pk_mul_f32 v[82:83], v[82:83], v[70:71]
; __device__ __forceinline__ unsigned cvt_pk_bf16(float lo, float hi) { unsigned r; asm volatile("v_cvt_pk_bf16_f32 %0, %1, %2" : "=v"(r) : "v"(lo), "v"(hi)); return r; }
; __device__ __forceinline__ float sigmoidf_(float x) { return __builtin_amdgcn_rcpf(1.0f + __expf(-x)); }
; __device__ __forceinline__ float dpp_ror1(float x) { return __int_as_float(__builtin_amdgcn_update_dpp(0, __float_as_int(x), 0x121, 0xF, 0xF, true)); }
; __device__ __forceinline__ float dpp_ror2(float x) { return __int_as_float(__builtin_amdgcn_update_dpp(0, __float_as_int(x), 0x122, 0xF, 0xF, true)); }
;     __device__ __forceinline__ void operator()(const f32x4 (&acc)[2][2][4][2], const Unit& u, int wr, int wc, int fr, int fq) const {
;     ...
;                 for (int n = 0; n < 2; ++n)
; #pragma unroll
;                     for (int i = 0; i < 4; ++i) {
;                         const float cur = acc[ai][0][m][n][i], prv = (m > 0) ? acc[ai][0][m > 0 ? m - 1 : 0][n][i] : cur;
;                         const float r1c = dpp_ror1(cur), r1p = dpp_ror1(prv), r2c = dpp_ror2(cur), r2p = dpp_ror2(prv);
;                         const float tm1 = f1 ? r1c : r1p, tm2 = f2 ? r2c : r2p;
;                         const float cv = w0[n][i] * tm2 + w1[n][i] * tm1 + w2[n][i] * cur;
;                         hg[4 * n + i] = cv * sigmoidf_(cv) * acc[ai][1][m][n][i];
;                     }
;                 if (m == 0 && fr < 2) {
;                     const f32x4 a0 = acc[ai][0][0][0], a1 = acc[ai][0][0][1], v0 = acc[ai][1][0][0], v1 = acc[ai][1][0][1];
;                     u32x4 wa, wv; wa.x = cvt_pk_bf16(a0[0], a0[1]); wa.y = cvt_pk_bf16(a0[2], a0[3]); wa.z = cvt_pk_bf16(a1[0], a1[1]); wa.w = cvt_pk_bf16(a1[2], a1[3]);
;                     wv.x = cvt_pk_bf16(v0[0], v0[1]); wv.y = cvt_pk_bf16(v0[2], v0[3]); wv.z = cvt_pk_bf16(v1[0], v1[1]); wv.w = cvt_pk_bf16(v1[2], v1[3]);
;                     *(u32x4*)(side + ((size_t)blk * 6 + 2 + fr) * ldh + ch0) = wa; *(u32x4*)(side + ((size_t)blk * 6 + 4 + fr) * ldh + ch0) = wv;
;                 } else {
;                     u32x4 w; w.x = cvt_pk_bf16(hg[0], hg[1]); w.y = cvt_pk_bf16(hg[2], hg[3]); w.z = cvt_pk_bf16(hg[4], hg[5]); w.w = cvt_pk_bf16(hg[6], hg[7]);
;                     *(u32x4*)(HG + row * ldh + ch0) = w;
	v_pk_mul_f32 v[84:85], v[84:85], v[72:73]
	v_pk_mul_f32 v[70:71], v[196:197], v[42:43]
	v_pk_mul_f32 v[72:73], v[198:199], v[44:45]
	v_fmac_f32_dpp v70, v42, v236 row_ror:1 row_mask:0xf bank_mask:0xf
	v_fmac_f32_dpp v71, v43, v237 row_ror:1 row_mask:0xf bank_mask:0xf
	v_fmac_f32_dpp v72, v44, v238 row_ror:1 row_mask:0xf bank_mask:0xf
	v_fmac_f32_dpp v73, v45, v239 row_ror:1 row_mask:0xf bank_mask:0xf
	v_fmac_f32_dpp v70, v42, v228 row_ror:2 row_mask:0xf bank_mask:0xf
	v_fmac_f32_dpp v71, v43, v229 row_ror:2 row_mask:0xf bank_mask:0xf
	v_fmac_f32_dpp v72, v44, v230 row_ror:2 row_mask:0xf bank_mask:0xf
	v_fmac_f32_dpp v73, v45, v231 row_ror:2 row_mask:0xf bank_mask:0xf
	v_pk_mul_f32 v[200:201], v[70:71], s[14:15]
	v_pk_mul_f32 v[202:203], v[72:73], s[14:15]
	v_exp_f32_e32 v200, v200
	v_exp_f32_e32 v201, v201
	v_exp_f32_e32 v202, v202
	v_exp_f32_e32 v203, v203
	v_pk_add_f32 v[200:201], v[200:201], s[24:25]
	v_pk_add_f32 v[202:203], v[202:203], s[24:25]
	v_rcp_f32_e32 v200, v200
	v_rcp_f32_e32 v201, v201
	v_rcp_f32_e32 v202, v202
	v_rcp_f32_e32 v203, v203
	v_pk_mul_f32 v[70:71], v[70:71], v[200:201]
	v_pk_mul_f32 v[72:73], v[72:73], v[202:203]
	v_pk_mul_f32 v[78:79], v[78:79], v[70:71]
	v_pk_mul_f32 v[80:81], v[80:81], v[72:73]
	v_cvt_pk_bf16_f32 v82, v82, v83
	v_cvt_pk_bf16_f32 v83, v84, v85
	v_cvt_pk_bf16_f32 v84, v78, v79
	v_cvt_pk_bf16_f32 v85, v80, v81
	v_add_co_u32_e32 v170, vcc, 0x1ae000, v170
	v_addc_co_u32_e32 v171, vcc, 0, v171, vcc
	s_and_b64 exec, s[22:23], s[40:41]
	global_store_dwordx4 v[170:171], v[82:85], off
	s_mov_b64 exec, s[22:23]
	v_cndmask_b32_e64 v200, v58, v62, s[16:17]
	v_cndmask_b32_e64 v201, v59, v63, s[16:17]
	v_cndmask_b32_e64 v202, v60, v64, s[16:17]
	v_cndmask_b32_e64 v203, v61, v65, s[16:17]
	v_cndmask_b32_e64 v204, v58, v62, s[42:43]
	v_cndmask_b32_e64 v205, v59, v63, s[42:43]
	v_cndmask_b32_e64 v206, v60, v64, s[42:43]
	v_cndmask_b32_e64 v207, v61, v65, s[42:43]
	v_pk_mul_f32 v[70:71], v[192:193], v[58:59]
	v_pk_mul_f32 v[72:73], v[194:195], v[60:61]
	v_fmac_f32_dpp v70, v200, v232 row_ror:1 row_mask:0xf bank_mask:0xf
	v_fmac_f32_dpp v71, v201, v233 row_ror:1 row_mask:0xf bank_mask:0xf
	v_fmac_f32_dpp v72, v202, v234 row_ror:1 row_mask:0xf bank_mask:0xf
	v_fmac_f32_dpp v73, v203, v235 row_ror:1 row_mask:0xf bank_mask:0xf
	v_fmac_f32_dpp v70, v204, v224 row_ror:2 row_mask:0xf bank_mask:0xf
	v_fmac_f32_dpp v71, v205, v225 row_ror:2 row_mask:0xf bank_mask:0xf
	v_fmac_f32_dpp v72, v206, v226 row_ror:2 row_mask:0xf bank_mask:0xf
	v_fmac_f32_dpp v73, v207, v227 row_ror:2 row_mask:0xf bank_mask:0xf
	v_pk_mul_f32 v[200:201], v[70:71], s[14:15]
	v_pk_mul_f32 v[202:203], v[72:73], s[14:15]
	v_exp_f32_e32 v200, v200
	v_exp_f32_e32 v201, v201
	v_exp_f32_e32 v202, v202
	v_exp_f32_e32 v203, v203
	v_pk_add_f32 v[200:201], v[200:201], s[24:25]
	v_pk_add_f32 v[202:203], v[202:203], s[24:25]
	v_rcp_f32_e32 v200, v200
	v_rcp_f32_e32 v201, v201
	v_rcp_f32_e32 v202, v202
	v_rcp_f32_e32 v203, v203
	v_pk_mul_f32 v[70:71], v[70:71], v[200:201]
	v_pk_mul_f32 v[72:73], v[72:73], v[202:203]
	v_pk_mul_f32 v[46:47], v[46:47], v[70:71]
	v_pk_mul_f32 v[48:49], v[48:49], v[72:73]
	v_cndmask_b32_e64 v200, v38, v42, s[16:17]
	v_cndmask_b32_e64 v201, v39, v43, s[16:17]
	v_cndmask_b32_e64 v202, v40, v44, s[16:17]
	v_cndmask_b32_e64 v203, v41, v45, s[16:17]
	v_cndmask_b32_e64 v204, v38, v42, s[42:43]
	v_cndmask_b32_e64 v205, v39, v43, s[42:43]
	v_cndmask_b32_e64 v206, v40, v44, s[42:43]
	v_cndmask_b32_e64 v207, v41, v45, s[42:43]
	v_pk_mul_f32 v[70:71], v[196:197], v[38:39]
	v_pk_mul_f32 v[72:73], v[198:199], v[40:41]
	v_fmac_f32_dpp v70, v200, v236 row_ror:1 row_mask:0xf bank_mask:0xf
	v_fmac_f32_dpp v71, v201, v237 row_ror:1 row_mask:0xf bank_mask:0xf
	v_fmac_f32_dpp v72, v202, v238 row_ror:1 row_mask:0xf bank_mask:0xf
	v_fmac_f32_dpp v73, v203, v239 row_ror:1 row_mask:0xf bank_mask:0xf
	v_fmac_f32_dpp v70, v204, v228 row_ror:2 row_mask:0xf bank_mask:0xf
	v_fmac_f32_dpp v71, v205, v229 row_ror:2 row_mask:0xf bank_mask:0xf
	v_fmac_f32_dpp v72, v206, v230 row_ror:2 row_mask:0xf bank_mask:0xf
	v_fmac_f32_dpp v73, v207, v231 row_ror:2 row_mask:0xf bank_mask:0xf
	v_pk_mul_f32 v[200:201], v[70:71], s[14:15]
	v_pk_mul_f32 v[202:203], v[72:73], s[14:15]
	v_exp_f32_e32 v200, v200
	v_exp_f32_e32 v201, v201
	v_exp_f32_e32 v202, v202
	v_exp_f32_e32 v203, v203
	v_pk_add_f32 v[200:201], v[200:201], s[24:25]
	v_pk_add_f32 v[202:203], v[202:203], s[24:25]
	v_rcp_f32_e32 v200, v200
	v_rcp_f32_e32 v201, v201
	v_rcp_f32_e32 v202, v202
	v_rcp_f32_e32 v203, v203
	v_pk_mul_f32 v[70:71], v[70:71], v[200:201]
	v_pk_mul_f32 v[72:73], v[72:73], v[202:203]
	v_pk_mul_f32 v[34:35], v[34:35], v[70:71]
	v_pk_mul_f32 v[36:37], v[36:37], v[72:73]
	v_cvt_pk_bf16_f32 v46, v46, v47
	v_cvt_pk_bf16_f32 v47, v48, v49
	v_cvt_pk_bf16_f32 v48, v34, v35
	v_cvt_pk_bf16_f32 v49, v36, v37
	v_add_co_u32_e32 v170, vcc, 0x56000, v170
	v_addc_co_u32_e32 v171, vcc, 0, v171, vcc
	global_store_dwordx4 v[170:171], v[46:49], off
	v_cndmask_b32_e64 v200, v30, v58, s[16:17]
	v_cndmask_b32_e64 v201, v31, v59, s[16:17]
	v_cndmask_b32_e64 v202, v32, v60, s[16:17]
	v_cndmask_b32_e64 v203, v33, v61, s[16:17]
	v_cndmask_b32_e64 v204, v30, v58, s[42:43]
	v_cndmask_b32_e64 v205, v31, v59, s[42:43]
	v_cndmask_b32_e64 v206, v32, v60, s[42:43]
	v_cndmask_b32_e64 v207, v33, v61, s[42:43]
	v_pk_mul_f32 v[70:71], v[192:193], v[30:31]
	v_pk_mul_f32 v[72:73], v[194:195], v[32:33]
	v_fmac_f32_dpp v70, v200, v232 row_ror:1 row_mask:0xf bank_mask:0xf
	v_fmac_f32_dpp v71, v201, v233 row_ror:1 row_mask:0xf bank_mask:0xf
	v_fmac_f32_dpp v72, v202, v234 row_ror:1 row_mask:0xf bank_mask:0xf
;     __device__ __forceinline__ void operator()(const f32x4 (&acc)[2][2][4][2], const Unit& u, int wr, int wc, int fr, int fq) const {
;     ...
;                 for (int n = 0; n < 2; ++n)
; #pragma unroll
;                     for (int i = 0; i < 4; ++i) {
;                         const float cur = acc[ai][0][m][n][i], prv = (m > 0) ? acc[ai][0][m > 0 ? m - 1 : 0][n][i] : cur;
;                         const float r1c = dpp_ror1(cur), r1p = dpp_ror1(prv), r2c = dpp_ror2(cur), r2p = dpp_ror2(prv);
;                         const float tm1 = f1 ? r1c : r1p, tm2 = f2 ? r2c : r2p;
;                         const float cv = w0[n][i] * tm2 + w1[n][i] * tm1 + w2[n][i] * cur;
;                         hg[4 * n + i] = cv * sigmoidf_(cv) * acc[ai][1][m][n][i];
;                     }
;                 if (m == 0 && fr < 2) {
;                     const f32x4 a0 = acc[ai][0][0][0], a1 = acc[ai][0][0][1], v0 = acc[ai][1][0][0], v1 = acc[ai][1][0][1];
;                     u32x4 wa, wv; wa.x = cvt_pk_bf16(a0[0], a0[1]); wa.y = cvt_pk_bf16(a0[2], a0[3]); wa.z = cvt_pk_bf16(a1[0], a1[1]); wa.w = cvt_pk_bf16(a1[2], a1[3]);
;                     wv.x = cvt_pk_bf16(v0[0], v0[1]); wv.y = cvt_pk_bf16(v0[2], v0[3]); wv.z = cvt_pk_bf16(v1[0], v1[1]); wv.w = cvt_pk_bf16(v1[2], v1[3]);
;                     *(u32x4*)(side + ((size_t)blk * 6 + 2 + fr) * ldh + ch0) = wa; *(u32x4*)(side + ((size_t)blk * 6 + 4 + fr) * ldh + ch0) = wv;
;                 } else {
;                     u32x4 w; w.x = cvt_pk_bf16(hg[0], hg[1]); w.y = cvt_pk_bf16(hg[2], hg[3]); w.z = cvt_pk_bf16(hg[4], hg[5]); w.w = cvt_pk_bf16(hg[6], hg[7]);
;                     *(u32x4*)(HG + row * ldh + ch0) = w;
;                 }
;                 if (m == 3 && fr >= 14) {
;                     const f32x4 a0 = acc[ai][0][3][0], a1 = acc[ai][0][3][1];
;                     u32x4 wa; wa.x = cvt_pk_bf16(a0[0], a0[1]); wa.y = cvt_pk_bf16(a0[2], a0[3]); wa.z = cvt_pk_bf16(a1[0], a1[1]); wa.w = cvt_pk_bf16(a1[2], a1[3]);
;                     *(u32x4*)(side + ((size_t)blk * 6 + (fr - 14)) * ldh + ch0) = wa;
;                 }
; template <class Epi, class Sched, bool ALIGN_EPI = false, bool SP2 = false>
; __device__ __forceinline__ void gemm_phase(PG8_LAS unsigned char* lds, const Gemm g, const Sched& S, const Epi& E) {
;     ...
;         if (!has_next) break;
; #pragma unroll
;         for (int a = 0; a < 2; ++a)
; #pragma unroll
	v_fmac_f32_dpp v73, v203, v235 row_ror:1 row_mask:0xf bank_mask:0xf
	v_fmac_f32_dpp v70, v204, v224 row_ror:2 row_mask:0xf bank_mask:0xf
	v_fmac_f32_dpp v71, v205, v225 row_ror:2 row_mask:0xf bank_mask:0xf
	v_fmac_f32_dpp v72, v206, v226 row_ror:2 row_mask:0xf bank_mask:0xf
	v_fmac_f32_dpp v73, v207, v227 row_ror:2 row_mask:0xf bank_mask:0xf
	v_pk_mul_f32 v[200:201], v[70:71], s[14:15]
	v_pk_mul_f32 v[202:203], v[72:73], s[14:15]
	v_exp_f32_e32 v200, v200
	v_exp_f32_e32 v201, v201
	v_exp_f32_e32 v202, v202
	v_exp_f32_e32 v203, v203
	v_pk_add_f32 v[200:201], v[200:201], s[24:25]
	v_pk_add_f32 v[202:203], v[202:203], s[24:25]
	v_rcp_f32_e32 v200, v200
	v_rcp_f32_e32 v201, v201
	v_rcp_f32_e32 v202, v202
	v_rcp_f32_e32 v203, v203
	v_pk_mul_f32 v[70:71], v[70:71], v[200:201]
	v_pk_mul_f32 v[72:73], v[72:73], v[202:203]
	v_pk_mul_f32 v[26:27], v[26:27], v[70:71]
	v_pk_mul_f32 v[28:29], v[28:29], v[72:73]
	v_cndmask_b32_e64 v200, v22, v38, s[16:17]
	v_cndmask_b32_e64 v201, v23, v39, s[16:17]
	v_cndmask_b32_e64 v202, v24, v40, s[16:17]
	v_cndmask_b32_e64 v203, v25, v41, s[16:17]
	v_cndmask_b32_e64 v204, v22, v38, s[42:43]
	v_cndmask_b32_e64 v205, v23, v39, s[42:43]
	v_cndmask_b32_e64 v206, v24, v40, s[42:43]
	v_cndmask_b32_e64 v207, v25, v41, s[42:43]
	v_pk_mul_f32 v[70:71], v[196:197], v[22:23]
	v_pk_mul_f32 v[72:73], v[198:199], v[24:25]
	v_fmac_f32_dpp v70, v200, v236 row_ror:1 row_mask:0xf bank_mask:0xf
	v_fmac_f32_dpp v71, v201, v237 row_ror:1 row_mask:0xf bank_mask:0xf
	v_fmac_f32_dpp v72, v202, v238 row_ror:1 row_mask:0xf bank_mask:0xf
	v_fmac_f32_dpp v73, v203, v239 row_ror:1 row_mask:0xf bank_mask:0xf
	v_fmac_f32_dpp v70, v204, v228 row_ror:2 row_mask:0xf bank_mask:0xf
	v_fmac_f32_dpp v71, v205, v229 row_ror:2 row_mask:0xf bank_mask:0xf
	v_fmac_f32_dpp v72, v206, v230 row_ror:2 row_mask:0xf bank_mask:0xf
	v_fmac_f32_dpp v73, v207, v231 row_ror:2 row_mask:0xf bank_mask:0xf
	v_pk_mul_f32 v[200:201], v[70:71], s[14:15]
	v_pk_mul_f32 v[202:203], v[72:73], s[14:15]
	v_exp_f32_e32 v200, v200
	v_exp_f32_e32 v201, v201
	v_exp_f32_e32 v202, v202
	v_exp_f32_e32 v203, v203
	v_pk_add_f32 v[200:201], v[200:201], s[24:25]
	v_pk_add_f32 v[202:203], v[202:203], s[24:25]
	v_rcp_f32_e32 v200, v200
	v_rcp_f32_e32 v201, v201
	v_rcp_f32_e32 v202, v202
	v_rcp_f32_e32 v203, v203
	v_pk_mul_f32 v[70:71], v[70:71], v[200:201]
	v_pk_mul_f32 v[72:73], v[72:73], v[202:203]
	v_pk_mul_f32 v[18:19], v[18:19], v[70:71]
	v_pk_mul_f32 v[20:21], v[20:21], v[72:73]
	v_cvt_pk_bf16_f32 v26, v26, v27
	v_cvt_pk_bf16_f32 v27, v28, v29
	v_cvt_pk_bf16_f32 v28, v18, v19
	v_cvt_pk_bf16_f32 v29, v20, v21
	v_add_co_u32_e32 v170, vcc, 0x56000, v170
	v_addc_co_u32_e32 v171, vcc, 0, v171, vcc
	global_store_dwordx4 v[170:171], v[26:29], off
	v_cndmask_b32_e64 v200, v10, v30, s[16:17]
	v_cndmask_b32_e64 v201, v11, v31, s[16:17]
	v_cndmask_b32_e64 v202, v12, v32, s[16:17]
	v_cndmask_b32_e64 v203, v13, v33, s[16:17]
	v_cndmask_b32_e64 v204, v10, v30, s[42:43]
	v_cndmask_b32_e64 v205, v11, v31, s[42:43]
	v_cndmask_b32_e64 v206, v12, v32, s[42:43]
	v_cndmask_b32_e64 v207, v13, v33, s[42:43]
	v_pk_mul_f32 v[70:71], v[192:193], v[10:11]
	v_pk_mul_f32 v[72:73], v[194:195], v[12:13]
	v_fmac_f32_dpp v70, v200, v232 row_ror:1 row_mask:0xf bank_mask:0xf
	v_fmac_f32_dpp v71, v201, v233 row_ror:1 row_mask:0xf bank_mask:0xf
	v_fmac_f32_dpp v72, v202, v234 row_ror:1 row_mask:0xf bank_mask:0xf
	v_fmac_f32_dpp v73, v203, v235 row_ror:1 row_mask:0xf bank_mask:0xf
	v_fmac_f32_dpp v70, v204, v224 row_ror:2 row_mask:0xf bank_mask:0xf
	v_fmac_f32_dpp v71, v205, v225 row_ror:2 row_mask:0xf bank_mask:0xf
	v_fmac_f32_dpp v72, v206, v226 row_ror:2 row_mask:0xf bank_mask:0xf
	v_fmac_f32_dpp v73, v207, v227 row_ror:2 row_mask:0xf bank_mask:0xf
	v_pk_mul_f32 v[200:201], v[70:71], s[14:15]
	v_pk_mul_f32 v[202:203], v[72:73], s[14:15]
	v_exp_f32_e32 v200, v200
	v_exp_f32_e32 v201, v201
	v_exp_f32_e32 v202, v202
	v_exp_f32_e32 v203, v203
	v_pk_add_f32 v[200:201], v[200:201], s[24:25]
	v_pk_add_f32 v[202:203], v[202:203], s[24:25]
	v_rcp_f32_e32 v200, v200
	v_rcp_f32_e32 v201, v201
	v_rcp_f32_e32 v202, v202
	v_rcp_f32_e32 v203, v203
	v_pk_mul_f32 v[70:71], v[70:71], v[200:201]
	v_pk_mul_f32 v[72:73], v[72:73], v[202:203]
	v_pk_mul_f32 v[14:15], v[14:15], v[70:71]
	v_pk_mul_f32 v[16:17], v[16:17], v[72:73]
	v_cndmask_b32_e64 v200, v6, v22, s[16:17]
	v_cndmask_b32_e64 v201, v7, v23, s[16:17]
	v_cndmask_b32_e64 v202, v8, v24, s[16:17]
	v_cndmask_b32_e64 v203, v9, v25, s[16:17]
	v_cndmask_b32_e64 v204, v6, v22, s[42:43]
	v_cndmask_b32_e64 v205, v7, v23, s[42:43]
	v_cndmask_b32_e64 v206, v8, v24, s[42:43]
	v_cndmask_b32_e64 v207, v9, v25, s[42:43]
	v_pk_mul_f32 v[70:71], v[196:197], v[6:7]
	v_pk_mul_f32 v[72:73], v[198:199], v[8:9]
	v_fmac_f32_dpp v70, v200, v236 row_ror:1 row_mask:0xf bank_mask:0xf
	v_fmac_f32_dpp v71, v201, v237 row_ror:1 row_mask:0xf bank_mask:0xf
	v_fmac_f32_dpp v72, v202, v238 row_ror:1 row_mask:0xf bank_mask:0xf
	v_fmac_f32_dpp v73, v203, v239 row_ror:1 row_mask:0xf bank_mask:0xf
	v_fmac_f32_dpp v70, v204, v228 row_ror:2 row_mask:0xf bank_mask:0xf
	v_fmac_f32_dpp v71, v205, v229 row_ror:2 row_mask:0xf bank_mask:0xf
	v_fmac_f32_dpp v72, v206, v230 row_ror:2 row_mask:0xf bank_mask:0xf
	v_fmac_f32_dpp v73, v207, v231 row_ror:2 row_mask:0xf bank_mask:0xf
	v_pk_mul_f32 v[200:201], v[70:71], s[14:15]
	v_pk_mul_f32 v[202:203], v[72:73], s[14:15]
	v_exp_f32_e32 v200, v200
	v_exp_f32_e32 v201, v201
	v_exp_f32_e32 v202, v202
	v_exp_f32_e32 v203, v203
	v_pk_add_f32 v[200:201], v[200:201], s[24:25]
	v_pk_add_f32 v[202:203], v[202:203], s[24:25]
	v_rcp_f32_e32 v200, v200
	v_rcp_f32_e32 v201, v201
	v_rcp_f32_e32 v202, v202
	v_rcp_f32_e32 v203, v203
	v_pk_mul_f32 v[70:71], v[70:71], v[200:201]
	v_pk_mul_f32 v[72:73], v[72:73], v[202:203]
	v_pk_mul_f32 v[2:3], v[2:3], v[70:71]
	v_pk_mul_f32 v[4:5], v[4:5], v[72:73]
	v_cvt_pk_bf16_f32 v14, v14, v15
	v_cvt_pk_bf16_f32 v15, v16, v17
	v_cvt_pk_bf16_f32 v16, v2, v3
	v_cvt_pk_bf16_f32 v17, v4, v5
	v_add_co_u32_e32 v170, vcc, 0x56000, v170
	v_addc_co_u32_e32 v171, vcc, 0, v171, vcc
	global_store_dwordx4 v[170:171], v[14:17], off
	v_cvt_pk_bf16_f32 v154, v10, v11
	v_cvt_pk_bf16_f32 v155, v12, v13
	v_cvt_pk_bf16_f32 v156, v6, v7
	v_cvt_pk_bf16_f32 v157, v8, v9
	v_add_co_u32_e32 v188, vcc, 0xffff5400, v190
	v_addc_co_u32_e32 v189, vcc, -1, v191, vcc
	s_and_b64 exec, s[22:23], s[42:43]
	global_store_dwordx4 v[188:189], v[154:157], off
	s_mov_b64 exec, s[22:23]
	s_andn2_b64 vcc, exec, s[20:21]
	s_mov_b64 s[20:21], -1
	s_cbranch_vccnz .LBB0_699
	s_andn2_b64 vcc, exec, s[46:47]
	s_cbranch_vccnz .LBB0_698
	s_barrier
	s_branch .LBB0_698
